# S3 entry: rmsnorm-stat butterfly xor-1/2/4/8 levels use DPP movs instead of ds_bpermute
# speedup vs baseline: 1.0025x; 1.0025x over previous
; __device__ __forceinline__ int opaque_tid() { int t = threadIdx.x; asm volatile("" : "+v"(t)); return t; }
; __device__ __forceinline__ float wave_sum(float v) {
; #pragma unroll
;     for (int o = 1; o < 64; o <<= 1) v += __shfl_xor(v, o);
;     return v;
; }
; __global__ void __launch_bounds__(NTHR) mega_fwd(Params p) {
;     ...
;             const int tid = opaque_tid(), lane = tid & 63, wave = __builtin_amdgcn_readfirstlane(tid >> 6), gw = bx * NWAVES + wave; (void)tid; (void)lane; (void)gw;
;             const float lam_init = l == 0 ? 0.2f : 0.35550906759096934f;
;             float lam; { const float* lp = p.diff_lambda + l * 256; const float sa = wave_sum(lp[lane] * lp[64 + lane]), sb = wave_sum(lp[128 + lane] * lp[192 + lane]); lam = expf(sa) - expf(sb) + lam_init; }
;             constexpr float C64 = 0.125f * 1.4426950408889634f, THR64 = att::THR / 0.125f;
;             constexpr float SC128 = 0.08838834764831845f, C128 = SC128 * 1.4426950408889634f, THR128 = att::THR / SC128;
;             const int r32 = lane & 31, hi = lane >> 5;
.LBB0_296:
	s_or_b64 exec, exec, s[0:1]
	s_xor_b64 s[0:1], s[12:13], -1
	v_writelane_b32 v255, s0, 16
	v_readlane_b32 s12, v254, 62
	v_readlane_b32 s13, v254, 63
	v_writelane_b32 v255, s1, 17
	v_readlane_b32 s0, v254, 58
	v_readlane_b32 s1, v254, 59
	s_xor_b64 s[0:1], s[0:1], -1
	v_writelane_b32 v255, s0, 18
	s_mov_b32 s5, s13
	v_mov_b32_e32 v154, v188
	v_writelane_b32 v255, s1, 19
	s_waitcnt lgkmcnt(0)
	v_readlane_b32 s14, v255, 0
	v_readlane_b32 s15, v255, 1
	v_readlane_b32 s16, v255, 2
	v_readlane_b32 s17, v255, 3
	v_readlane_b32 s18, v255, 4
	v_readlane_b32 s19, v255, 5
	v_readlane_b32 s20, v255, 6
	v_readlane_b32 s21, v255, 7
	v_readlane_b32 s22, v255, 8
	v_readlane_b32 s23, v255, 9
	v_readlane_b32 s24, v255, 10
	v_readlane_b32 s25, v255, 11
	v_readlane_b32 s26, v255, 12
	v_readlane_b32 s27, v255, 13
	v_readlane_b32 s12, v251, 17
	v_readlane_b32 s2, v255, 14
	v_readlane_b32 s13, v251, 18
	v_readlane_b32 s14, v251, 19
	v_readlane_b32 s15, v251, 20
	v_readlane_b32 s16, v251, 21
	v_readlane_b32 s17, v251, 22
	v_readlane_b32 s18, v251, 23
	v_readlane_b32 s19, v251, 24
	v_readlane_b32 s20, v251, 25
	v_readlane_b32 s21, v251, 26
	v_readlane_b32 s22, v251, 27
	v_readlane_b32 s23, v251, 28
	s_lshl_b32 s4, s2, 8
	v_readlane_b32 s24, v251, 29
	v_readlane_b32 s25, v251, 30
	v_readlane_b32 s26, v251, 31
	v_readlane_b32 s27, v251, 32
	s_mov_b64 s[12:13], s[16:17]
	s_lshl_b64 s[0:1], s[4:5], 2
	s_mov_b64 s[14:15], s[18:19]
	s_mov_b64 s[16:17], s[20:21]
	s_mov_b64 s[18:19], s[22:23]
	s_mov_b64 s[20:21], s[24:25]
	s_mov_b64 s[22:23], s[26:27]
	s_barrier
	s_add_u32 s0, s22, s0
	s_addc_u32 s1, s23, s1
	v_and_b32_e32 v0, 63, v154
	v_lshlrev_b32_e32 v0, 2, v0
	global_load_dword v2, v0, s[0:1]
	global_load_dword v3, v0, s[0:1] offset:256
	global_load_dword v4, v0, s[0:1] offset:512
	s_nop 0
	global_load_dword v0, v0, s[0:1] offset:768
	v_and_b32_e32 v5, 64, v192
	v_xor_b32_e32 v6, 1, v192
	v_add_u32_e32 v5, 64, v5
	v_cmp_lt_i32_e32 vcc, v6, v5
	v_xor_b32_e32 v7, 2, v192
	v_xor_b32_e32 v8, 4, v192
	v_cndmask_b32_e32 v6, v192, v6, vcc
	v_lshlrev_b32_e32 v162, 2, v6
	v_cmp_lt_i32_e32 vcc, v7, v5
	v_readlane_b32 s3, v255, 15
	s_lshl_b32 s4, s2, 11
	v_cndmask_b32_e32 v7, v192, v7, vcc
	v_lshlrev_b32_e32 v178, 2, v7
	v_cmp_lt_i32_e32 vcc, v8, v5
	s_mov_b32 s1, s5
	v_writelane_b32 v254, s0, 62
	v_cndmask_b32_e32 v8, v192, v8, vcc
	v_lshlrev_b32_e32 v179, 2, v8
	v_writelane_b32 v255, s2, 0
	v_writelane_b32 v255, s3, 1
	v_xor_b32_e32 v9, 8, v192
	v_writelane_b32 v255, s4, 2
	v_cmp_lt_i32_e32 vcc, v9, v5
	v_writelane_b32 v255, s5, 3
	v_writelane_b32 v255, s6, 4
	v_cndmask_b32_e32 v9, v192, v9, vcc
	v_lshlrev_b32_e32 v180, 2, v9
	v_writelane_b32 v255, s7, 5
	v_writelane_b32 v255, s8, 6
	v_writelane_b32 v255, s9, 7
	v_xor_b32_e32 v10, 16, v192
	v_writelane_b32 v255, s10, 8
	v_cmp_lt_i32_e32 vcc, v10, v5
	v_writelane_b32 v255, s11, 9
	v_writelane_b32 v255, s12, 10
	v_writelane_b32 v255, s13, 11
	v_writelane_b32 v255, s14, 12
	v_writelane_b32 v255, s15, 13
	s_lshl_b64 s[4:5], s[4:5], 2
	v_readlane_b32 s0, v252, 56
	v_xor_b32_e32 v11, 32, v192
	s_add_u32 s0, s0, s4
	v_writelane_b32 v255, s0, 20
	v_readlane_b32 s0, v252, 57
	v_writelane_b32 v255, s4, 21
	s_addc_u32 s0, s0, s5
	v_writelane_b32 v254, s1, 63
	v_writelane_b32 v255, s5, 22
	v_writelane_b32 v255, s0, 23
	s_lshl_b32 s0, s2, 9
	v_writelane_b32 v255, s0, 24
	v_readfirstlane_b32 s33, v154
	v_cmp_eq_u32_e64 s[38:39], 0, v154
	v_writelane_b32 v255, s1, 25
	v_readlane_b32 s0, v252, 58
	v_readlane_b32 s1, v252, 59
	s_waitcnt vmcnt(2)
	v_mul_f32_e32 v6, v2, v3
	s_nop 1
	v_mov_b32_dpp v6, v6 quad_perm:[1,0,3,2] row_mask:0xf bank_mask:0xf
	s_waitcnt vmcnt(0)
	v_mul_f32_e32 v12, v4, v0
	s_nop 1
	v_mov_b32_dpp v12, v12 quad_perm:[1,0,3,2] row_mask:0xf bank_mask:0xf
	s_waitcnt lgkmcnt(1)
	v_fmac_f32_e32 v6, v2, v3
	v_cndmask_b32_e32 v3, v192, v10, vcc
	s_waitcnt lgkmcnt(0)
	v_fmac_f32_e32 v12, v4, v0
	s_nop 1
	v_mov_b32_dpp v0, v6 quad_perm:[2,3,0,1] row_mask:0xf bank_mask:0xf
	s_nop 1
	v_mov_b32_dpp v2, v12 quad_perm:[2,3,0,1] row_mask:0xf bank_mask:0xf
	v_lshlrev_b32_e32 v187, 2, v3
	v_cmp_lt_i32_e32 vcc, v11, v5
	s_waitcnt lgkmcnt(1)
	v_add_f32_e32 v0, v6, v0
	s_waitcnt lgkmcnt(0)
	v_add_f32_e32 v2, v12, v2
	s_nop 1
	v_mov_b32_dpp v4, v0 row_half_mirror row_mask:0xf bank_mask:0xf
	s_nop 1
	v_mov_b32_dpp v6, v2 row_half_mirror row_mask:0xf bank_mask:0xf
	v_cndmask_b32_e32 v5, v192, v11, vcc
	v_lshlrev_b32_e32 v186, 2, v5
	s_and_b64 vcc, exec, s[0:1]
	s_waitcnt lgkmcnt(1)
	v_add_f32_e32 v0, v0, v4
	s_waitcnt lgkmcnt(0)
	v_add_f32_e32 v2, v2, v6
	s_nop 1
	v_mov_b32_dpp v4, v0 row_mirror row_mask:0xf bank_mask:0xf
	s_nop 1
	v_mov_b32_dpp v6, v2 row_mirror row_mask:0xf bank_mask:0xf
	s_waitcnt lgkmcnt(1)
	v_add_f32_e32 v0, v0, v4
	s_waitcnt lgkmcnt(0)
	v_add_f32_e32 v2, v2, v6
	ds_bpermute_b32 v3, v187, v0
	ds_bpermute_b32 v4, v187, v2
	s_waitcnt lgkmcnt(1)
	v_add_f32_e32 v0, v0, v3
	s_waitcnt lgkmcnt(0)
	v_add_f32_e32 v10, v2, v4
	ds_bpermute_b32 v11, v186, v0
	ds_bpermute_b32 v12, v186, v10
	s_cbranch_vccz .LBB0_366
	v_readlane_b32 s12, v254, 62
	v_readlane_b32 s13, v254, 63
	v_readlane_b32 s14, v255, 0
	v_readlane_b32 s15, v255, 1
	v_readlane_b32 s16, v255, 2
	v_readlane_b32 s17, v255, 3
	v_readlane_b32 s18, v255, 4
	v_readlane_b32 s19, v255, 5
	v_readlane_b32 s2, v255, 14
	s_mov_b32 s5, s13
	v_readlane_b32 s20, v255, 6
	v_readlane_b32 s21, v255, 7
	v_readlane_b32 s22, v255, 8
	v_readlane_b32 s23, v255, 9
	v_readlane_b32 s24, v255, 10
	v_readlane_b32 s25, v255, 11
	v_readlane_b32 s26, v255, 12
	v_readlane_b32 s27, v255, 13
	s_mov_b32 s1, s13
	v_readlane_b32 s3, v255, 15
	v_writelane_b32 v254, s4, 62
	s_mul_i32 s0, s2, 0x3e00
	s_lshl_b64 s[0:1], s[0:1], 2
	v_writelane_b32 v255, s6, 0
	v_writelane_b32 v255, s7, 1
	v_writelane_b32 v255, s8, 2
	v_writelane_b32 v255, s9, 3
	v_writelane_b32 v255, s10, 4
	v_writelane_b32 v255, s11, 5
	v_writelane_b32 v255, s12, 6
	v_writelane_b32 v255, s13, 7
	v_writelane_b32 v255, s14, 8
	v_writelane_b32 v255, s15, 9
	v_writelane_b32 v255, s16, 10
	v_writelane_b32 v255, s17, 11
	v_writelane_b32 v255, s18, 12
	v_writelane_b32 v255, s19, 13
	v_readlane_b32 s12, v251, 33
	v_readlane_b32 s14, v251, 35
	v_writelane_b32 v254, s5, 63
	v_readlane_b32 s15, v251, 36
	s_add_u32 s2, s14, s0
	s_addc_u32 s3, s15, s1
	v_readlane_b32 s0, v254, 60
	v_readlane_b32 s4, v255, 20
	v_readlane_b32 s1, v254, 61
	s_add_u32 s4, s4, s0
	v_readlane_b32 s0, v255, 23
	s_addc_u32 s5, s0, s1
	s_mov_b32 s0, 0
	s_mov_b64 s[6:7], -1
	v_readlane_b32 s13, v251, 34
	v_readlane_b32 s16, v251, 37
	v_readlane_b32 s17, v251, 38
	v_readlane_b32 s18, v251, 39
	v_readlane_b32 s19, v251, 40
	v_readlane_b32 s20, v251, 41
	v_readlane_b32 s21, v251, 42
	v_readlane_b32 s22, v251, 43
	v_readlane_b32 s23, v251, 44
	v_readlane_b32 s24, v251, 45
	v_readlane_b32 s25, v251, 46
	v_readlane_b32 s26, v251, 47
	v_readlane_b32 s27, v251, 48
	s_branch .LBB0_299
